# previous + mixer items re-indexed per XCD so the GEMM1>mixer barrier is XCD-local too (8 of 14 barriers local)
# speedup vs baseline: 1.0298x; 1.0029x over previous
; #define LAS __attribute__((address_space(3)))
; __device__ __forceinline__ void attn_item(LAS unsigned char* lds, const bf16* P, bf16* Y, const float* qg, const float* kg, const float* sinks, int item, int tid) {
;     const int hkv = item & 1, nb = (item >> 1) & 15, b = item >> 5;
;     const int R0 = b * SEQ + nb * 128;
;     LAS bf16* Ks = (LAS bf16*)lds; LAS bf16* Vt = (LAS bf16*)(lds + 36864);
;     v4u qraw[4][2];
;     { const int w_ = tid >> 6, ln = tid & 63; const bf16* qp = P + (size_t)(R0 + (w_ & 1) * 64 + (ln & 15)) * PP + (hkv * 4 + (w_ >> 1)) * 64 + 8 * (ln >> 4);
; #pragma unroll
;       for (int it = 0; it < 4; ++it) { qraw[it][0] = *(const v4u*)(qp + (size_t)(16 * it) * PP); qraw[it][1] = *(const v4u*)(qp + (size_t)(16 * it) * PP + 32); } }
; #pragma unroll
;     for (int i = 0; i < 4; ++i) {
;         const int task = tid + 512 * i, key = task >> 3, c = task & 7; const bool ok = (nb > 0) || (key >= 128);
;         v4u kr = {0u, 0u, 0u, 0u}, vr = {0u, 0u, 0u, 0u};
;         if (ok) { const bf16* rp = P + (size_t)(R0 - 128 + key) * PP + hkv * 64 + 8 * c; kr = *(const v4u*)(rp + C_K); vr = *(const v4u*)(rp + C_V); }
;         float kf[8];
; #pragma unroll
;         for (int e = 0; e < 4; ++e) { kf[2 * e] = bflo(kr[e]); kf[2 * e + 1] = bfhi(kr[e]); }
;         float ss = 0.f;
; #pragma unroll
;         for (int e = 0; e < 8; ++e) ss += kf[e] * kf[e];
;         ss += __shfl_xor(ss, 1); ss += __shfl_xor(ss, 2); ss += __shfl_xor(ss, 4);
;         const float rs = rsqrtf(ss * (1.f / 64.f) + EPS);
;         const f32x4 g0 = *(const f32x4*)(kg + 8 * c), g1 = *(const f32x4*)(kg + 8 * c + 4);
;         v4u kw; kw.x = cvt_pk_bf16(kf[0] * rs * g0.x, kf[1] * rs * g0.y); kw.y = cvt_pk_bf16(kf[2] * rs * g0.z, kf[3] * rs * g0.w);
;         kw.z = cvt_pk_bf16(kf[4] * rs * g1.x, kf[5] * rs * g1.y); kw.w = cvt_pk_bf16(kf[6] * rs * g1.z, kf[7] * rs * g1.w);
;         *(LAS v4u*)(Ks + key * 72 + 8 * c) = kw;
; #pragma unroll
;         for (int e = 0; e < 4; ++e) { Vt[(8 * c + 2 * e) * 264 + key] = (bf16)(vr[e] & 0xffffu); Vt[(8 * c + 2 * e + 1) * 264 + key] = (bf16)(vr[e] >> 16); }
;     }
;     __syncthreads();
;     const int w = tid >> 6, lane = tid & 63, fr = lane & 15, fq = lane >> 4, g = w >> 1, h = hkv * 4 + g, half = w & 1;
;     const float slope2 = exp2f(-(float)(h + 1)) * LOG2E, sink2 = sinks[h] * LOG2E;
;     f32x4 qgv[4];
; #pragma unroll
.LBB0_126:
	s_andn2_b64 vcc, exec, s[18:19]
	s_cbranch_vccnz .LBB0_145
	s_cmpk_gt_i32 s21, 0x2ff
	s_cbranch_scc1 .LBB0_145
	v_readlane_b32 s2, v254, 31
	v_readlane_b32 s3, v254, 32
	s_mov_b32 s29, s3
	s_lshl_b32 s28, s91, 9
	s_lshl_b64 s[2:3], s[28:29], 2
	s_add_u32 s2, s80, s2
	s_addc_u32 s3, s81, s3
	s_lshl_b32 s28, s91, 10
	s_lshl_b64 s[18:19], s[28:29], 2
	s_add_u32 s40, s48, s18
	s_addc_u32 s41, s49, s19
	s_lshl_b32 s28, s91, 6
	s_lshl_b64 s[18:19], s[28:29], 2
	v_and_b32_e32 v4, 48, v241
	s_waitcnt lgkmcnt(0)
	v_mov_b32_e32 v5, v2
	s_add_u32 s22, s74, s18
	v_lshl_add_u64 v[100:101], s[2:3], 0, v[4:5]
	v_lshl_add_u64 v[4:5], s[26:27], 0, v[4:5]
	s_mov_b64 s[2:3], 0x1c00000
	s_addc_u32 s23, s75, s19
	v_lshl_add_u64 v[102:103], v[4:5], 0, s[2:3]
	v_lshlrev_b32_e32 v5, 3, v242
	s_add_u32 s18, s76, s18
	v_and_b32_e32 v5, 56, v5
	s_addc_u32 s19, s77, s19
	v_lshlrev_b32_e32 v14, 2, v5
	v_mov_b32_e32 v15, v2
	v_lshl_add_u64 v[104:105], s[18:19], 0, v[14:15]
	v_lshlrev_b32_e32 v14, 1, v5
	v_add_u32_e32 v7, 0, v14
	v_lshl_add_u64 v[106:107], s[16:17], 0, v[14:15]
	v_add_u32_e32 v14, 0x400, v242
	v_bfe_u32 v3, v242, 4, 2
	s_movk_i32 s2, 0x20e
	v_add_u32_e32 v11, 0x200, v242
	v_ashrrev_i32_e32 v203, 3, v14
	v_add_u32_e32 v14, 0x600, v242
	v_and_b32_e32 v186, 15, v242
	v_ashrrev_i32_e32 v193, 3, v242
	v_mad_u32_u24 v5, v5, s2, v7
	v_ashrrev_i32_e32 v195, 3, v11
	v_ashrrev_i32_e32 v205, 3, v14
	v_lshlrev_b32_e32 v14, 5, v3
	v_lshl_add_u32 v194, v193, 1, v5
	v_lshl_add_u32 v202, v195, 1, v5
	v_lshl_add_u32 v204, v203, 1, v5
	v_lshl_add_u32 v206, v205, 1, v5
	v_lshl_add_u64 v[108:109], s[22:23], 0, v[14:15]
	v_or_b32_e32 v5, 0x80, v186
	v_lshlrev_b32_e32 v14, 2, v3
	v_sub_u32_e32 v5, v5, v14
	s_movk_i32 s2, 0x80
	v_subrev_co_u32_e64 v14, s[46:47], s2, v5
	s_movk_i32 s3, 0x90
	v_cvt_f32_u32_e32 v208, v14
	v_add_u32_e32 v14, -1, v5
	s_mov_b32 s25, s29
	v_mul_lo_u32 v9, v193, s3
	v_mul_lo_u32 v11, v195, s3
	v_mul_lo_u32 v16, v203, s3
	v_mul_lo_u32 v17, v205, s3
	s_movk_i32 s3, 0x81
	v_cvt_f32_u32_e32 v209, v14
	v_add_u32_e32 v14, -2, v5
	s_lshl_b32 s28, s91, 3
	v_writelane_b32 v254, s24, 31
	v_subrev_co_u32_e64 v15, s[50:51], s3, v5
	v_cmp_gt_u32_e64 s[54:55], s2, v14
	v_cvt_f32_u32_e32 v211, v14
	v_add_u32_e32 v14, -3, v5
	v_writelane_b32 v254, s25, 32
	s_lshl_b64 s[24:25], s[28:29], 2
	v_bfe_u32 v1, v242, 6, 1
	v_cmp_lt_u32_e64 s[52:53], s2, v5
	v_cvt_f32_u32_e32 v210, v15
	v_add_u32_e32 v15, 0xffffff7e, v5
	v_cmp_gt_u32_e64 s[58:59], s2, v14
	s_movk_i32 s2, 0x82
	s_add_u32 s42, s78, s24
	s_movk_i32 s18, 0x7f
	v_cvt_f32_u32_e32 v212, v15
	v_add_u32_e32 v15, 0xffffff7d, v5
	v_cmp_lt_u32_e64 s[60:61], s2, v5
	v_lshlrev_b32_e32 v216, 7, v1
	s_movk_i32 s2, 0x210
	s_addc_u32 s43, s79, s25
	v_lshlrev_b32_e32 v12, 3, v3
	v_cvt_f32_ubyte0_e32 v207, v5
	v_cmp_lt_u32_e64 s[48:49], s18, v5
	v_cmp_lt_u32_e64 s[56:57], s3, v5
	v_cvt_f32_u32_e32 v213, v14
	v_cvt_f32_u32_e32 v214, v15
	v_mad_u32_u24 v5, v186, s2, v216
	s_add_i32 s2, 0, 0x9000
	v_lshrrev_b32_e32 v0, 2, v241
	v_lshlrev_b32_e32 v4, 7, v186
	v_add3_u32 v217, v5, v12, s2
	v_mul_u32_u24_e32 v5, 0x90, v186
	s_movk_i32 s2, 0x2400
	v_and_b32_e32 v0, 12, v0
	v_or_b32_e32 v6, 0x800, v4
	v_or_b32_e32 v8, 0x1000, v4
	v_or_b32_e32 v10, 0x1800, v4
	v_lshl_or_b32 v191, v1, 6, v186
	v_mov_b32_e32 v13, v2
	v_lshlrev_b32_e32 v215, 2, v1
	v_mad_u32_u24 v1, v1, s2, v5
	v_lshlrev_b32_e32 v3, 4, v3
	v_lshlrev_b32_e32 v187, 1, v241
	v_lshl_add_u32 v188, v241, 3, 0
	v_and_b32_e32 v189, 48, v242
	v_mul_u32_u24_e32 v190, 0x110, v186
	v_ashrrev_i32_e32 v192, 7, v242
	v_cmp_lt_i32_e64 s[64:65], s18, v193
	v_cmp_lt_i32_e64 s[84:85], s18, v195
	v_cmp_lt_i32_e64 s[90:91], s18, v203
	v_cmp_lt_i32_e64 s[92:93], s18, v205
	v_lshl_add_u64 v[110:111], s[14:15], 0, v[12:13]
	v_add3_u32 v218, v1, v3, 0
	v_lshlrev_b32_e32 v112, 1, v4
	v_lshlrev_b32_e32 v114, 1, v0
	v_lshlrev_b32_e32 v116, 1, v6
	v_lshlrev_b32_e32 v118, 1, v8
	v_lshlrev_b32_e32 v120, 1, v10
	v_lshlrev_b32_e32 v122, 1, v12
	v_add_u32_e32 v219, v7, v9
	v_add_u32_e32 v220, v7, v11
	v_add_u32_e32 v221, v7, v16
	v_add_u32_e32 v222, v7, v17
	s_and_b32 s25, s21, 7
	s_lshl_b32 s25, s25, 6
	s_lshr_b32 s24, s21, 3
	s_add_i32 s25, s25, s24
	s_lshl_b32 s24, s25, 6
	s_branch .LBB0_130
.LBB0_129:
	s_cmpk_gt_i32 s25, 0x1ff
	s_cbranch_scc1 .LBB0_144
	s_bitcmp1_b32 s25, 5
	s_cbranch_scc1 mixr_sgu
	s_add_i32 s25, s25, 32
	s_branch mixr_next
mixr_sgu:
	s_lshr_b32 s2, s25, 6
	s_lshl_b32 s2, s2, 5
	s_and_b32 s25, s25, 31
	s_add_i32 s25, s25, s2
	s_addk_i32 s25, 0x200
mixr_next:
	s_lshl_b32 s24, s25, 6

; __device__ __forceinline__ float bflo(unsigned u) { return __uint_as_float(u << 16); }
; __device__ __forceinline__ float bfhi(unsigned u) { return __uint_as_float(u & 0xffff0000u); }
; #define LAS __attribute__((address_space(3)))
; __device__ __forceinline__ void attn_item(LAS unsigned char* lds, const bf16* P, bf16* Y, const float* qg, const float* kg, const float* sinks, int item, int tid) {
;     const int hkv = item & 1, nb = (item >> 1) & 15, b = item >> 5;
;     const int R0 = b * SEQ + nb * 128;
;     LAS bf16* Ks = (LAS bf16*)lds; LAS bf16* Vt = (LAS bf16*)(lds + 36864);
;     v4u qraw[4][2];
;     { const int w_ = tid >> 6, ln = tid & 63; const bf16* qp = P + (size_t)(R0 + (w_ & 1) * 64 + (ln & 15)) * PP + (hkv * 4 + (w_ >> 1)) * 64 + 8 * (ln >> 4);
; #pragma unroll
;       for (int it = 0; it < 4; ++it) { qraw[it][0] = *(const v4u*)(qp + (size_t)(16 * it) * PP); qraw[it][1] = *(const v4u*)(qp + (size_t)(16 * it) * PP + 32); } }
; #pragma unroll
;     for (int i = 0; i < 4; ++i) {
;         const int task = tid + 512 * i, key = task >> 3, c = task & 7; const bool ok = (nb > 0) || (key >= 128);
;         v4u kr = {0u, 0u, 0u, 0u}, vr = {0u, 0u, 0u, 0u};
;         if (ok) { const bf16* rp = P + (size_t)(R0 - 128 + key) * PP + hkv * 64 + 8 * c; kr = *(const v4u*)(rp + C_K); vr = *(const v4u*)(rp + C_V); }
;         float kf[8];
; #pragma unroll
;         for (int e = 0; e < 4; ++e) { kf[2 * e] = bflo(kr[e]); kf[2 * e + 1] = bfhi(kr[e]); }
;         float ss = 0.f;
; #pragma unroll
;         for (int e = 0; e < 8; ++e) ss += kf[e] * kf[e];
;         ss += __shfl_xor(ss, 1); ss += __shfl_xor(ss, 2); ss += __shfl_xor(ss, 4);
;         const float rs = rsqrtf(ss * (1.f / 64.f) + EPS);
;         const f32x4 g0 = *(const f32x4*)(kg + 8 * c), g1 = *(const f32x4*)(kg + 8 * c + 4);
.LBB0_132:
	s_andn2_b64 vcc, exec, s[18:19]
	s_cbranch_vccnz .LBB0_129
	s_bfe_u32 s3, s25, 0x40001
	s_lshl_b32 s22, s25, 6
	s_and_b32 s18, s22, 0xfffff800
	s_lshl_b32 s19, s3, 7
	s_and_b32 s2, s25, 1
	s_or_b32 s23, s19, s18
	v_or_b32_e32 v3, s23, v191
	v_mov_b64_e32 v[0:1], s[16:17]
	v_lshl_add_u32 v46, s2, 2, v192
	v_mad_i64_i32 v[4:5], s[18:19], v3, s36, v[0:1]
	v_lshlrev_b32_e32 v0, 6, v46
	v_ashrrev_i32_e32 v1, 31, v0
	v_lshl_add_u64 v[4:5], v[0:1], 1, v[4:5]
	v_mov_b32_e32 v123, v2
	v_lshl_add_u64 v[20:21], v[4:5], 0, v[122:123]
	global_load_dwordx4 v[160:163], v[104:105], off offset:16
	global_load_dwordx4 v[164:167], v[104:105], off
	v_ashrrev_i32_e32 v47, 31, v46
	v_lshl_add_u64 v[36:37], v[46:47], 2, s[42:43]
	global_load_dword v184, v[36:37], off
	global_load_dwordx4 v[168:171], v[108:109], off
	global_load_dwordx4 v[172:175], v[108:109], off offset:16
	global_load_dwordx4 v[176:179], v[108:109], off offset:128
	global_load_dwordx4 v[180:183], v[108:109], off offset:144
	s_mov_b32 s18, 0x17000
	v_add_co_u32_e32 v8, vcc, s18, v20
	s_mov_b32 s18, 0x2e000
	s_nop 0
	v_addc_co_u32_e32 v9, vcc, 0, v21, vcc
	v_add_co_u32_e32 v16, vcc, s18, v20
	s_mov_b32 s18, 0x45000
	s_nop 0
	v_addc_co_u32_e32 v17, vcc, 0, v21, vcc
	v_add_co_u32_e32 v24, vcc, s18, v20
	global_load_dwordx4 v[32:35], v[20:21], off
	global_load_dwordx4 v[28:31], v[20:21], off offset:64
	v_addc_co_u32_e32 v25, vcc, 0, v21, vcc
	global_load_dwordx4 v[4:7], v[8:9], off
	s_nop 0
	global_load_dwordx4 v[8:11], v[8:9], off offset:64
	s_nop 0
	global_load_dwordx4 v[12:15], v[16:17], off
	s_nop 0
	global_load_dwordx4 v[16:19], v[16:17], off offset:64
	s_nop 0
	global_load_dwordx4 v[20:23], v[24:25], off
	s_nop 0
	global_load_dwordx4 v[24:27], v[24:25], off offset:64
	v_readlane_b32 s18, v254, 31
	s_cmp_lg_u32 s3, 0
	v_readlane_b32 s19, v254, 32
	s_cselect_b64 s[44:45], -1, 0
	s_mov_b32 s29, s19
	s_lshl_b32 s28, s2, 7
	v_writelane_b32 v254, s18, 31
	s_addk_i32 s23, 0xff80
	v_lshl_add_u64 v[48:49], v[106:107], 0, s[28:29]
	v_writelane_b32 v254, s19, 32
	s_or_b64 s[28:29], s[64:65], s[44:45]
	v_mov_b32_e32 v64, 0
	v_mov_b32_e32 v65, 0
	v_mov_b32_e32 v66, 0
	v_mov_b32_e32 v67, 0
	v_mov_b32_e32 v68, 0
	v_mov_b32_e32 v69, 0
	v_mov_b32_e32 v70, 0
	v_mov_b32_e32 v71, 0
	v_mov_b32_e32 v76, 0
	v_mov_b32_e32 v77, 0
	v_mov_b32_e32 v78, 0
	v_mov_b32_e32 v79, 0
	v_mov_b32_e32 v80, 0
	v_mov_b32_e32 v81, 0
	v_mov_b32_e32 v82, 0
	v_mov_b32_e32 v83, 0
	v_mov_b32_e32 v84, 0
	v_mov_b32_e32 v85, 0
	v_mov_b32_e32 v86, 0
	v_mov_b32_e32 v87, 0
	v_mov_b32_e32 v88, 0
	v_mov_b32_e32 v89, 0
	v_mov_b32_e32 v90, 0
	v_mov_b32_e32 v91, 0
	v_mov_b32_e32 v92, 0
	v_mov_b32_e32 v93, 0
	v_mov_b32_e32 v94, 0
	v_mov_b32_e32 v95, 0
	v_mov_b32_e32 v96, 0
	v_mov_b32_e32 v97, 0
	v_mov_b32_e32 v98, 0
	v_mov_b32_e32 v99, 0
	s_or_b64 s[28:29], s[44:45], s[64:65]
	v_add_u32_e32 v37, s23, v193
	v_mad_i64_i32 v[38:39], s[18:19], v37, s36, v[48:49]
	s_and_saveexec_b64 s[34:35], s[28:29]
	global_load_dwordx4 v[64:67], v[38:39], off offset:1024
	global_load_dwordx4 v[68:71], v[38:39], off offset:1280
	s_or_b64 exec, exec, s[34:35]
	s_or_b64 s[28:29], s[44:45], s[84:85]
	v_add_u32_e32 v37, s23, v195
	v_mad_i64_i32 v[40:41], s[18:19], v37, s36, v[48:49]
	s_and_saveexec_b64 s[34:35], s[28:29]
	global_load_dwordx4 v[76:79], v[40:41], off offset:1024
	global_load_dwordx4 v[80:83], v[40:41], off offset:1280
	s_or_b64 exec, exec, s[34:35]
	s_or_b64 s[28:29], s[44:45], s[90:91]
	v_add_u32_e32 v37, s23, v203
	v_mad_i64_i32 v[42:43], s[18:19], v37, s36, v[48:49]
	s_and_saveexec_b64 s[34:35], s[28:29]
	global_load_dwordx4 v[84:87], v[42:43], off offset:1024
	global_load_dwordx4 v[88:91], v[42:43], off offset:1280
	s_or_b64 exec, exec, s[34:35]
	s_or_b64 s[28:29], s[44:45], s[92:93]
	v_add_u32_e32 v37, s23, v205
	v_mad_i64_i32 v[44:45], s[18:19], v37, s36, v[48:49]
	s_and_saveexec_b64 s[34:35], s[28:29]
	global_load_dwordx4 v[92:95], v[44:45], off offset:1024
	global_load_dwordx4 v[96:99], v[44:45], off offset:1280
	s_or_b64 exec, exec, s[34:35]
	v_and_b32_e32 v3, 64, v235
	v_add_u32_e32 v3, 64, v3
	v_xor_b32_e32 v37, 1, v235
	v_cmp_lt_i32_e32 vcc, v37, v3
	s_nop 1
	v_cndmask_b32_e32 v37, v235, v37, vcc
	v_lshlrev_b32_e32 v47, 2, v37
	v_xor_b32_e32 v37, 2, v235
	v_cmp_lt_i32_e32 vcc, v37, v3
	s_nop 1
	v_cndmask_b32_e32 v37, v235, v37, vcc
	v_lshlrev_b32_e32 v50, 2, v37
	v_xor_b32_e32 v37, 4, v235
	v_cmp_lt_i32_e32 vcc, v37, v3
	s_nop 1
	v_cndmask_b32_e32 v37, v235, v37, vcc
	v_lshlrev_b32_e32 v51, 2, v37
	s_waitcnt vmcnt(6)
	v_lshlrev_b32_e32 v56, 16, v64
	v_and_b32_e32 v57, 0xffff0000, v64
	v_lshlrev_b32_e32 v59, 16, v65
	v_and_b32_e32 v58, 0xffff0000, v65
	v_lshlrev_b32_e32 v61, 16, v66
	v_and_b32_e32 v60, 0xffff0000, v66
	v_lshlrev_b32_e32 v63, 16, v67
	v_and_b32_e32 v62, 0xffff0000, v67
	v_mul_f32_e32 v52, v56, v56
	v_mul_f32_e32 v37, v57, v57
	v_add_f32_e32 v52, v52, v37
	v_mul_f32_e32 v37, v59, v59
	v_add_f32_e32 v52, v37, v52
	v_mul_f32_e32 v37, v58, v58
	v_add_f32_e32 v52, v37, v52
	v_mul_f32_e32 v37, v61, v61
	v_add_f32_e32 v52, v37, v52
	v_mul_f32_e32 v37, v60, v60
	v_add_f32_e32 v52, v37, v52
	v_mul_f32_e32 v37, v63, v63
	v_add_f32_e32 v52, v37, v52
	v_mul_f32_e32 v37, v62, v62
	v_add_f32_e32 v52, v37, v52
	s_waitcnt vmcnt(4)
	v_lshlrev_b32_e32 v56, 16, v76
	v_and_b32_e32 v57, 0xffff0000, v76
	v_lshlrev_b32_e32 v59, 16, v77
	v_and_b32_e32 v58, 0xffff0000, v77
	v_lshlrev_b32_e32 v61, 16, v78
	v_and_b32_e32 v60, 0xffff0000, v78
	v_lshlrev_b32_e32 v63, 16, v79
	v_and_b32_e32 v62, 0xffff0000, v79
	v_mul_f32_e32 v53, v56, v56
	v_mul_f32_e32 v37, v57, v57
	v_add_f32_e32 v53, v53, v37
	v_mul_f32_e32 v37, v59, v59
	v_add_f32_e32 v53, v37, v53
	v_mul_f32_e32 v37, v58, v58
	v_add_f32_e32 v53, v37, v53
	v_mul_f32_e32 v37, v61, v61
	v_add_f32_e32 v53, v37, v53
	v_mul_f32_e32 v37, v60, v60
	v_add_f32_e32 v53, v37, v53
	v_mul_f32_e32 v37, v63, v63
	v_add_f32_e32 v53, v37, v53
	v_mul_f32_e32 v37, v62, v62
	v_add_f32_e32 v53, v37, v53
	s_waitcnt vmcnt(2)
; __device__ __forceinline__ unsigned cvt_pk_bf16(float lo, float hi) { unsigned r; asm volatile("v_cvt_pk_bf16_f32 %0, %1, %2" : "=v"(r) : "v"(lo), "v"(hi)); return r; }
; #define LAS __attribute__((address_space(3)))
; __device__ __forceinline__ void attn_item(LAS unsigned char* lds, const bf16* P, bf16* Y, const float* qg, const float* kg, const float* sinks, int item, int tid) {
;     ...
;         float ss = 0.f;
; #pragma unroll
;         for (int e = 0; e < 8; ++e) ss += kf[e] * kf[e];
;         ss += __shfl_xor(ss, 1); ss += __shfl_xor(ss, 2); ss += __shfl_xor(ss, 4);
;         const float rs = rsqrtf(ss * (1.f / 64.f) + EPS);
;         const f32x4 g0 = *(const f32x4*)(kg + 8 * c), g1 = *(const f32x4*)(kg + 8 * c + 4);
;         v4u kw; kw.x = cvt_pk_bf16(kf[0] * rs * g0.x, kf[1] * rs * g0.y); kw.y = cvt_pk_bf16(kf[2] * rs * g0.z, kf[3] * rs * g0.w);
;         kw.z = cvt_pk_bf16(kf[4] * rs * g1.x, kf[5] * rs * g1.y); kw.w = cvt_pk_bf16(kf[6] * rs * g1.z, kf[7] * rs * g1.w);
;         *(LAS v4u*)(Ks + key * 72 + 8 * c) = kw;
; #pragma unroll
;         for (int e = 0; e < 4; ++e) { Vt[(8 * c + 2 * e) * 264 + key] = (bf16)(vr[e] & 0xffffu); Vt[(8 * c + 2 * e + 1) * 264 + key] = (bf16)(vr[e] >> 16); }
	v_lshlrev_b32_e32 v56, 16, v84
	v_and_b32_e32 v57, 0xffff0000, v84
	v_lshlrev_b32_e32 v59, 16, v85
	v_and_b32_e32 v58, 0xffff0000, v85
	v_lshlrev_b32_e32 v61, 16, v86
	v_and_b32_e32 v60, 0xffff0000, v86
	v_lshlrev_b32_e32 v63, 16, v87
	v_and_b32_e32 v62, 0xffff0000, v87
	v_mul_f32_e32 v54, v56, v56
	v_mul_f32_e32 v37, v57, v57
	v_add_f32_e32 v54, v54, v37
	v_mul_f32_e32 v37, v59, v59
	v_add_f32_e32 v54, v37, v54
	v_mul_f32_e32 v37, v58, v58
	v_add_f32_e32 v54, v37, v54
	v_mul_f32_e32 v37, v61, v61
	v_add_f32_e32 v54, v37, v54
	v_mul_f32_e32 v37, v60, v60
	v_add_f32_e32 v54, v37, v54
	v_mul_f32_e32 v37, v63, v63
	v_add_f32_e32 v54, v37, v54
	v_mul_f32_e32 v37, v62, v62
	v_add_f32_e32 v54, v37, v54
	s_waitcnt vmcnt(0)
	v_lshlrev_b32_e32 v56, 16, v92
	v_and_b32_e32 v57, 0xffff0000, v92
	v_lshlrev_b32_e32 v59, 16, v93
	v_and_b32_e32 v58, 0xffff0000, v93
	v_lshlrev_b32_e32 v61, 16, v94
	v_and_b32_e32 v60, 0xffff0000, v94
	v_lshlrev_b32_e32 v63, 16, v95
	v_and_b32_e32 v62, 0xffff0000, v95
	v_mul_f32_e32 v55, v56, v56
	v_mul_f32_e32 v37, v57, v57
	v_add_f32_e32 v55, v55, v37
	v_mul_f32_e32 v37, v59, v59
	v_add_f32_e32 v55, v37, v55
	v_mul_f32_e32 v37, v58, v58
	v_add_f32_e32 v55, v37, v55
	v_mul_f32_e32 v37, v61, v61
	v_add_f32_e32 v55, v37, v55
	v_mul_f32_e32 v37, v60, v60
	v_add_f32_e32 v55, v37, v55
	v_mul_f32_e32 v37, v63, v63
	v_add_f32_e32 v55, v37, v55
	v_mul_f32_e32 v37, v62, v62
	v_add_f32_e32 v55, v37, v55
	ds_bpermute_b32 v40, v47, v52
	ds_bpermute_b32 v41, v47, v53
	ds_bpermute_b32 v42, v47, v54
	ds_bpermute_b32 v43, v47, v55
	s_waitcnt lgkmcnt(0)
	v_add_f32_e32 v52, v52, v40
	v_add_f32_e32 v53, v53, v41
	v_add_f32_e32 v54, v54, v42
	v_add_f32_e32 v55, v55, v43
	ds_bpermute_b32 v40, v50, v52
	ds_bpermute_b32 v41, v50, v53
	ds_bpermute_b32 v42, v50, v54
	ds_bpermute_b32 v43, v50, v55
	s_waitcnt lgkmcnt(0)
	v_add_f32_e32 v52, v52, v40
	v_add_f32_e32 v53, v53, v41
	v_add_f32_e32 v54, v54, v42
	v_add_f32_e32 v55, v55, v43
	ds_bpermute_b32 v40, v51, v52
	ds_bpermute_b32 v41, v51, v53
	ds_bpermute_b32 v42, v51, v54
	ds_bpermute_b32 v43, v51, v55
	s_waitcnt lgkmcnt(0)
	v_add_f32_e32 v52, v52, v40
	v_add_f32_e32 v53, v53, v41
	v_add_f32_e32 v54, v54, v42
	v_add_f32_e32 v55, v55, v43
	v_fmamk_f32 v52, v52, 0x3c800000, v196
	v_cmp_gt_f32_e32 vcc, s13, v52
	v_mul_f32_e32 v37, 0x4b800000, v52
	s_nop 0
	v_cndmask_b32_e32 v52, v52, v37, vcc
	v_rsq_f32_e32 v52, v52
	s_nop 0
	v_mul_f32_e32 v37, 0x45800000, v52
	v_cndmask_b32_e32 v52, v52, v37, vcc
	v_fmamk_f32 v53, v53, 0x3c800000, v196
	v_cmp_gt_f32_e32 vcc, s13, v53
	v_mul_f32_e32 v37, 0x4b800000, v53
	s_nop 0
	v_cndmask_b32_e32 v53, v53, v37, vcc
	v_rsq_f32_e32 v53, v53
	s_nop 0
	v_mul_f32_e32 v37, 0x45800000, v53
	v_cndmask_b32_e32 v53, v53, v37, vcc
	v_fmamk_f32 v54, v54, 0x3c800000, v196
	v_cmp_gt_f32_e32 vcc, s13, v54
	v_mul_f32_e32 v37, 0x4b800000, v54
	s_nop 0
	v_cndmask_b32_e32 v54, v54, v37, vcc
	v_rsq_f32_e32 v54, v54
	s_nop 0
	v_mul_f32_e32 v37, 0x45800000, v54
	v_cndmask_b32_e32 v54, v54, v37, vcc
	v_fmamk_f32 v55, v55, 0x3c800000, v196
	v_cmp_gt_f32_e32 vcc, s13, v55
	v_mul_f32_e32 v37, 0x4b800000, v55
	s_nop 0
	v_cndmask_b32_e32 v55, v55, v37, vcc
	v_rsq_f32_e32 v55, v55
	s_nop 0
	v_mul_f32_e32 v37, 0x45800000, v55
	v_cndmask_b32_e32 v55, v55, v37, vcc
	v_lshlrev_b32_e32 v56, 16, v64
	v_and_b32_e32 v57, 0xffff0000, v64
	v_lshlrev_b32_e32 v59, 16, v65
	v_and_b32_e32 v58, 0xffff0000, v65
	v_lshlrev_b32_e32 v61, 16, v66
	v_and_b32_e32 v60, 0xffff0000, v66
	v_lshlrev_b32_e32 v63, 16, v67
	v_and_b32_e32 v62, 0xffff0000, v67
	v_mul_f32_e32 v56, v52, v56
	v_mul_f32_e32 v56, v164, v56
	v_mul_f32_e32 v57, v52, v57
	v_mul_f32_e32 v57, v165, v57
	v_mul_f32_e32 v59, v52, v59
	v_mul_f32_e32 v59, v166, v59
	v_mul_f32_e32 v58, v52, v58
	v_mul_f32_e32 v58, v167, v58
	v_mul_f32_e32 v61, v52, v61
	v_mul_f32_e32 v61, v160, v61
	v_mul_f32_e32 v60, v52, v60
	v_mul_f32_e32 v60, v161, v60
	v_mul_f32_e32 v63, v52, v63
	v_mul_f32_e32 v63, v162, v63
	v_mul_f32_e32 v62, v52, v62
	v_mul_f32_e32 v62, v163, v62
	v_cvt_pk_bf16_f32 v40, v56, v57
	v_cvt_pk_bf16_f32 v41, v59, v58
	v_cvt_pk_bf16_f32 v42, v61, v60
	v_cvt_pk_bf16_f32 v43, v63, v62
	ds_write_b128 v219, v[40:43]
	ds_write_b16 v194, v68 offset:36864
	ds_write_b16_d16_hi v194, v68 offset:37392
	ds_write_b16 v194, v69 offset:37920
	ds_write_b16_d16_hi v194, v69 offset:38448
	ds_write_b16 v194, v70 offset:38976
	ds_write_b16_d16_hi v194, v70 offset:39504
	ds_write_b16 v194, v71 offset:40032
	ds_write_b16_d16_hi v194, v71 offset:40560
	v_lshlrev_b32_e32 v56, 16, v76
	v_and_b32_e32 v57, 0xffff0000, v76
	v_lshlrev_b32_e32 v59, 16, v77
	v_and_b32_e32 v58, 0xffff0000, v77
	v_lshlrev_b32_e32 v61, 16, v78
	v_and_b32_e32 v60, 0xffff0000, v78
	v_lshlrev_b32_e32 v63, 16, v79
	v_and_b32_e32 v62, 0xffff0000, v79
	v_mul_f32_e32 v56, v53, v56
	v_mul_f32_e32 v56, v164, v56
	v_mul_f32_e32 v57, v53, v57
	v_mul_f32_e32 v57, v165, v57
	v_mul_f32_e32 v59, v53, v59
	v_mul_f32_e32 v59, v166, v59
	v_mul_f32_e32 v58, v53, v58
	v_mul_f32_e32 v58, v167, v58
	v_mul_f32_e32 v61, v53, v61
	v_mul_f32_e32 v61, v160, v61
	v_mul_f32_e32 v60, v53, v60
	v_mul_f32_e32 v60, v161, v60
	v_mul_f32_e32 v63, v53, v63
	v_mul_f32_e32 v63, v162, v63
	v_mul_f32_e32 v62, v53, v62
	v_mul_f32_e32 v62, v163, v62
; #define LAS __attribute__((address_space(3)))
; __device__ __forceinline__ void attn_item(LAS unsigned char* lds, const bf16* P, bf16* Y, const float* qg, const float* kg, const float* sinks, int item, int tid) {
;     ...
;         *(LAS v4u*)(Ks + key * 72 + 8 * c) = kw;
; #pragma unroll
;         for (int e = 0; e < 4; ++e) { Vt[(8 * c + 2 * e) * 264 + key] = (bf16)(vr[e] & 0xffffu); Vt[(8 * c + 2 * e + 1) * 264 + key] = (bf16)(vr[e] >> 16); }
;     }
;     __syncthreads();
;     const int w = tid >> 6, lane = tid & 63, fr = lane & 15, fq = lane >> 4, g = w >> 1, h = hkv * 4 + g, half = w & 1;
;     const float slope2 = exp2f(-(float)(h + 1)) * LOG2E, sink2 = sinks[h] * LOG2E;
; __global__ void __launch_bounds__(NWAVES * 64, 2) fwd_kernel(Args args) {
;     ...
;                 for (int it = bid; it < 768; it += G) {
	v_cvt_pk_bf16_f32 v40, v56, v57
	v_cvt_pk_bf16_f32 v41, v59, v58
	v_cvt_pk_bf16_f32 v42, v61, v60
	v_cvt_pk_bf16_f32 v43, v63, v62
	ds_write_b128 v220, v[40:43]
	ds_write_b16 v202, v80 offset:36864
	ds_write_b16_d16_hi v202, v80 offset:37392
	ds_write_b16 v202, v81 offset:37920
	ds_write_b16_d16_hi v202, v81 offset:38448
	ds_write_b16 v202, v82 offset:38976
	ds_write_b16_d16_hi v202, v82 offset:39504
	ds_write_b16 v202, v83 offset:40032
	ds_write_b16_d16_hi v202, v83 offset:40560
	v_lshlrev_b32_e32 v56, 16, v84
	v_and_b32_e32 v57, 0xffff0000, v84
	v_lshlrev_b32_e32 v59, 16, v85
	v_and_b32_e32 v58, 0xffff0000, v85
	v_lshlrev_b32_e32 v61, 16, v86
	v_and_b32_e32 v60, 0xffff0000, v86
	v_lshlrev_b32_e32 v63, 16, v87
	v_and_b32_e32 v62, 0xffff0000, v87
	v_mul_f32_e32 v56, v54, v56
	v_mul_f32_e32 v56, v164, v56
	v_mul_f32_e32 v57, v54, v57
	v_mul_f32_e32 v57, v165, v57
	v_mul_f32_e32 v59, v54, v59
	v_mul_f32_e32 v59, v166, v59
	v_mul_f32_e32 v58, v54, v58
	v_mul_f32_e32 v58, v167, v58
	v_mul_f32_e32 v61, v54, v61
	v_mul_f32_e32 v61, v160, v61
	v_mul_f32_e32 v60, v54, v60
	v_mul_f32_e32 v60, v161, v60
	v_mul_f32_e32 v63, v54, v63
	v_mul_f32_e32 v63, v162, v63
	v_mul_f32_e32 v62, v54, v62
	v_mul_f32_e32 v62, v163, v62
	v_cvt_pk_bf16_f32 v40, v56, v57
	v_cvt_pk_bf16_f32 v41, v59, v58
	v_cvt_pk_bf16_f32 v42, v61, v60
	v_cvt_pk_bf16_f32 v43, v63, v62
	ds_write_b128 v221, v[40:43]
	ds_write_b16 v204, v88 offset:36864
	ds_write_b16_d16_hi v204, v88 offset:37392
	ds_write_b16 v204, v89 offset:37920
	ds_write_b16_d16_hi v204, v89 offset:38448
	ds_write_b16 v204, v90 offset:38976
	ds_write_b16_d16_hi v204, v90 offset:39504
	ds_write_b16 v204, v91 offset:40032
	ds_write_b16_d16_hi v204, v91 offset:40560
	v_lshlrev_b32_e32 v56, 16, v92
	v_and_b32_e32 v57, 0xffff0000, v92
	v_lshlrev_b32_e32 v59, 16, v93
	v_and_b32_e32 v58, 0xffff0000, v93
	v_lshlrev_b32_e32 v61, 16, v94
	v_and_b32_e32 v60, 0xffff0000, v94
	v_lshlrev_b32_e32 v63, 16, v95
	v_and_b32_e32 v62, 0xffff0000, v95
	v_mul_f32_e32 v56, v55, v56
	v_mul_f32_e32 v56, v164, v56
	v_mul_f32_e32 v57, v55, v57
	v_mul_f32_e32 v57, v165, v57
	v_mul_f32_e32 v59, v55, v59
	v_mul_f32_e32 v59, v166, v59
	v_mul_f32_e32 v58, v55, v58
	v_mul_f32_e32 v58, v167, v58
	v_mul_f32_e32 v61, v55, v61
	v_mul_f32_e32 v61, v160, v61
	v_mul_f32_e32 v60, v55, v60
	v_mul_f32_e32 v60, v161, v60
	v_mul_f32_e32 v63, v55, v63
	v_mul_f32_e32 v63, v162, v63
	v_mul_f32_e32 v62, v55, v62
	v_mul_f32_e32 v62, v163, v62
	v_cvt_pk_bf16_f32 v40, v56, v57
	v_cvt_pk_bf16_f32 v41, v59, v58
	v_cvt_pk_bf16_f32 v42, v61, v60
	v_cvt_pk_bf16_f32 v43, v63, v62
	ds_write_b128 v222, v[40:43]
	ds_write_b16 v206, v96 offset:36864
	ds_write_b16_d16_hi v206, v96 offset:37392
	ds_write_b16 v206, v97 offset:37920
	ds_write_b16_d16_hi v206, v97 offset:38448
	ds_write_b16 v206, v98 offset:38976
	ds_write_b16_d16_hi v206, v98 offset:39504
	ds_write_b16 v206, v99 offset:40032
	ds_write_b16_d16_hi v206, v99 offset:40560
	s_and_b32 s18, s24, 0xfffff800
	v_or_b32_e32 v44, s18, v191
	s_and_b32 s18, s22, 0x780
	v_or_b32_e32 v72, s18, v44
	s_mov_b32 s2, 0
	s_mov_b32 s18, 0x42fc0000
	s_cmp_eq_u32 s3, 0
	s_cselect_b64 s[62:63], -1, 0
	v_lshl_add_u64 v[74:75], v[0:1], 1, v[110:111]
	v_mov_b32_e32 v0, v218
	v_mov_b32_e32 v133, v215
	v_add_u32_e32 v36, 1, v46
	v_cvt_f32_i32_e32 v36, v36
	v_mov_b32_e32 v37, 0x42800000
	v_ashrrev_i32_e32 v47, 31, v46
	v_cmp_lt_f32_e32 vcc, s18, v36
	s_waitcnt lgkmcnt(0)
	s_barrier
	v_cndmask_b32_e32 v37, 0, v37, vcc
	v_sub_f32_e32 v36, v37, v36
	v_exp_f32_e32 v36, v36
	v_not_b32_e32 v37, 63
	v_cndmask_b32_e32 v37, 0, v37, vcc
	v_ldexp_f32 v52, v36, v37
	v_mov_b32_e32 v53, v184
	v_mov_b32_e32 v36, v168
	v_mov_b32_e32 v37, v169
	v_mov_b32_e32 v38, v170
	v_mov_b32_e32 v39, v171
	v_mov_b32_e32 v40, v172
	v_mov_b32_e32 v41, v173
	v_mov_b32_e32 v42, v174
	v_mov_b32_e32 v43, v175
	v_mov_b32_e32 v44, v176
	v_mov_b32_e32 v45, v177
	v_mov_b32_e32 v46, v178
	v_mov_b32_e32 v47, v179
	v_mov_b32_e32 v48, v180
	v_mov_b32_e32 v49, v181
	v_mov_b32_e32 v50, v182
	v_mov_b32_e32 v51, v183
	s_add_i32 s18, s25, 32
	s_bitcmp1_b32 s25, 5
	s_cbranch_scc0 mixr_pf_have
	s_lshr_b32 s18, s25, 6
	s_lshl_b32 s18, s18, 5
	s_and_b32 s19, s25, 31
	s_add_i32 s18, s18, s19
	s_addk_i32 s18, 0x200
mixr_pf_have:
	s_cmpk_gt_i32 s18, 0x2ff
	s_cbranch_scc1 .Lpf_done
	s_cmpk_gt_i32 s18, 0x1ff
	s_cbranch_scc1 .Lpf_sgu
	s_lshl_b32 s19, s18, 6
	s_and_b32 s28, s19, 0xfffff800
	s_bfe_u32 s29, s18, 0x40001
	s_lshl_b32 s29, s29, 7
	s_or_b32 s28, s28, s29
	s_and_b32 s29, s18, 1
	v_lshrrev_b32_e32 v164, 2, v242
	v_add_u32_e32 v164, s28, v164
	v_mul_lo_u32 v164, v164, s36
	v_and_b32_e32 v165, 3, v242
	v_lshlrev_b32_e32 v165, 7, v165
	s_lshl_b32 s19, s29, 9
	v_add3_u32 v164, v164, v165, s19
	v_mov_b32_e32 v165, 0
	v_lshl_add_u64 v[166:167], v[164:165], 0, s[16:17]
	global_load_dword v168, v[166:167], off
	v_lshrrev_b32_e32 v164, 1, v242
	v_add_u32_e32 v164, s28, v164
	v_subrev_u32_e32 v164, 0x80, v164
	v_max_i32_e32 v164, 0, v164
	v_mul_lo_u32 v164, v164, s36
	v_and_b32_e32 v165, 1, v242
	v_lshlrev_b32_e32 v165, 8, v165
	s_lshl_b32 s19, s29, 7
	s_addk_i32 s19, 0x400
	v_add3_u32 v164, v164, v165, s19
	v_mov_b32_e32 v165, 0
	v_lshl_add_u64 v[166:167], v[164:165], 0, s[16:17]
	global_load_dword v169, v[166:167], off
	s_branch .Lpf_done

; __global__ void __launch_bounds__(NWAVES * 64, 2) fwd_kernel(Args args) {
;     ...
;         if (ph + 1 < args.ph_hi || rep + 1 < nrep) { if (args.ph_hi > 1000) grid.sync(); else xcd_barrier(xb); } else __syncthreads();
cvx_decided:
	s_mov_b32 s2, 0x6ad4
	s_bitcmp1_b32 s2, s10
	s_cbranch_scc0 cvx_fullbar
	s_cmp_eq_u32 s101, 1
	s_cbranch_scc0 cvx_fullbar
	v_readlane_b32 s22, v253, 12
	v_readlane_b32 s23, v253, 13
	v_mov_b32_e32 v3, 0
	v_mov_b32_e32 v0, 1
	s_and_b32 s2, s89, 7
	s_lshl_b32 s2, s2, 7
	s_add_i32 s2, s2, 0x3600
	s_add_u32 s22, s22, s2
	s_addc_u32 s23, s23, 0
	global_atomic_add v1, v3, v0, s[22:23] sc0
	s_waitcnt vmcnt(0)
	v_readfirstlane_b32 s2, v1
	s_nop 0
	s_lshr_b32 s3, s2, 5
	s_add_i32 s3, s3, 1
	s_lshl_b32 s3, s3, 5
	s_mov_b32 s2, 0
